# MLA: 12-cycle issue bubbles every 6 VALU slots in the older half's softmax segment
# speedup vs baseline: 1.0242x; 1.0025x over previous
.Lmla_nowrite_A:
	s_waitcnt lgkmcnt(9)
	v_mfma_f32_32x32x16_bf16 v[64:79], v[178:181], v[100:103], v[64:79]
	s_waitcnt lgkmcnt(8)
	v_mfma_f32_32x32x16_bf16 v[48:63], v[198:201], v[100:103], v[48:63]
	s_setprio 0
	s_nop 10
	v_max_f32_e32 v172, v64, v65
	v_max3_f32 v173, v66, v67, v49
	v_max3_f32 v172, v172, v48, v50
	v_max3_f32 v172, v172, v51, v68
	v_max3_f32 v173, v173, v70, v71
	v_max3_f32 v172, v172, v69, v52
	s_nop 2
	v_max3_f32 v173, v173, v54, v55
	v_max3_f32 v172, v172, v53, v72
	v_max3_f32 v173, v173, v74, v75
	v_max3_f32 v172, v172, v73, v56
	v_max3_f32 v173, v173, v58, v59
	v_max3_f32 v172, v172, v57, v76
	s_nop 2
	v_max3_f32 v173, v173, v78, v79
	v_max3_f32 v172, v172, v77, v60
	v_max3_f32 v173, v173, v62, v63
	v_max3_f32 v172, v172, v61, v173
	v_mov_b32_e32 v173, v172
	s_nop 1
	v_permlane32_swap_b32_e32 v172, v173
	s_nop 2
	v_max_f32_e32 v177, v172, v173
	v_cmp_lt_f32_e32 vcc, s14, v177
	s_cbranch_vccz .Lmla_norescale_A
	v_max_f32_e32 v172, s15, v177
	v_max_f32_e32 v173, 0xc2c80000, v172
	v_exp_f32_e64 v173, -v173
	v_add_f32_e32 v156, v156, v172
	v_sub_f32_e32 v48, v48, v172
	s_nop 2
	v_sub_f32_e32 v49, v49, v172
	v_sub_f32_e32 v50, v50, v172
	v_sub_f32_e32 v51, v51, v172
	v_sub_f32_e32 v52, v52, v172
	v_sub_f32_e32 v53, v53, v172
	v_sub_f32_e32 v54, v54, v172
	s_nop 2
	v_sub_f32_e32 v55, v55, v172
	v_sub_f32_e32 v56, v56, v172
	v_sub_f32_e32 v57, v57, v172
	v_sub_f32_e32 v58, v58, v172
	v_sub_f32_e32 v59, v59, v172
	v_sub_f32_e32 v60, v60, v172
	s_nop 2
	v_sub_f32_e32 v61, v61, v172
	v_sub_f32_e32 v62, v62, v172
	v_sub_f32_e32 v63, v63, v172
	v_sub_f32_e32 v64, v64, v172
	v_sub_f32_e32 v65, v65, v172
	v_sub_f32_e32 v66, v66, v172
	s_nop 2
	v_sub_f32_e32 v67, v67, v172
	v_sub_f32_e32 v68, v68, v172
	v_sub_f32_e32 v69, v69, v172
	v_sub_f32_e32 v70, v70, v172
	v_sub_f32_e32 v71, v71, v172
	v_sub_f32_e32 v72, v72, v172
	s_nop 2
	v_sub_f32_e32 v73, v73, v172
	v_sub_f32_e32 v74, v74, v172
	v_sub_f32_e32 v75, v75, v172
	v_sub_f32_e32 v76, v76, v172
	v_sub_f32_e32 v77, v77, v172
	v_sub_f32_e32 v78, v78, v172
	s_nop 2
	v_sub_f32_e32 v79, v79, v172
	v_mul_f32_e32 v0, v0, v173
	v_mul_f32_e32 v1, v1, v173
	v_mul_f32_e32 v2, v2, v173
	v_mul_f32_e32 v3, v3, v173
	v_mul_f32_e32 v4, v4, v173
	s_nop 2
	v_mul_f32_e32 v5, v5, v173
	v_mul_f32_e32 v6, v6, v173
	v_mul_f32_e32 v7, v7, v173
	v_mul_f32_e32 v8, v8, v173
	v_mul_f32_e32 v9, v9, v173
	v_mul_f32_e32 v10, v10, v173
	s_nop 2
	v_mul_f32_e32 v11, v11, v173
	v_mul_f32_e32 v12, v12, v173
	v_mul_f32_e32 v13, v13, v173
	v_mul_f32_e32 v14, v14, v173
	v_mul_f32_e32 v15, v15, v173
	v_mul_f32_e32 v16, v16, v173
	s_nop 2
	v_mul_f32_e32 v17, v17, v173
	v_mul_f32_e32 v18, v18, v173
	v_mul_f32_e32 v19, v19, v173
	v_mul_f32_e32 v20, v20, v173
	v_mul_f32_e32 v21, v21, v173
	v_mul_f32_e32 v22, v22, v173
	s_nop 2
	v_mul_f32_e32 v23, v23, v173
	v_mul_f32_e32 v24, v24, v173
	v_mul_f32_e32 v25, v25, v173
	v_mul_f32_e32 v26, v26, v173
	v_mul_f32_e32 v27, v27, v173
	v_mul_f32_e32 v28, v28, v173
	s_nop 2
	v_mul_f32_e32 v29, v29, v173
	v_mul_f32_e32 v30, v30, v173
	v_mul_f32_e32 v31, v31, v173
	v_mul_f32_e32 v157, v157, v173
	v_sub_f32_e32 v32, 0, v156
	v_mov_b32_e32 v33, v32
	s_nop 2
	v_mov_b32_e32 v34, v32
	v_mov_b32_e32 v35, v32
	v_mov_b32_e32 v36, v32
	v_mov_b32_e32 v37, v32
	v_mov_b32_e32 v38, v32
	v_mov_b32_e32 v39, v32
	s_nop 2
	v_mov_b32_e32 v40, v32
	v_mov_b32_e32 v41, v32
	v_mov_b32_e32 v42, v32
	v_mov_b32_e32 v43, v32
	v_mov_b32_e32 v44, v32
	v_mov_b32_e32 v45, v32
	s_nop 2
	v_mov_b32_e32 v46, v32
	v_mov_b32_e32 v47, v32
.Lmla_norescale_A:
	v_exp_f32_e32 v64, v64
	v_exp_f32_e32 v65, v65
	v_exp_f32_e32 v66, v66
	s_nop 2
	v_exp_f32_e32 v67, v67
	v_exp_f32_e32 v68, v68
	v_exp_f32_e32 v69, v69
	s_nop 2
	v_exp_f32_e32 v70, v70
	v_exp_f32_e32 v71, v71
	v_cvt_pk_bf16_f32 v234, v64, v65
	v_cvt_pk_bf16_f32 v235, v66, v67
	s_nop 2
	v_cvt_pk_bf16_f32 v236, v68, v69
	v_cvt_pk_bf16_f32 v237, v70, v71
	v_exp_f32_e32 v72, v72
	v_exp_f32_e32 v73, v73
	s_nop 2
	v_exp_f32_e32 v74, v74
	v_exp_f32_e32 v75, v75
	v_exp_f32_e32 v76, v76
	s_nop 2
	v_exp_f32_e32 v77, v77
	v_exp_f32_e32 v78, v78
	v_exp_f32_e32 v79, v79
	s_nop 2
	v_cvt_pk_bf16_f32 v238, v72, v73
	v_cvt_pk_bf16_f32 v239, v74, v75
	v_cvt_pk_bf16_f32 v240, v76, v77
	v_cvt_pk_bf16_f32 v241, v78, v79
	v_exp_f32_e32 v48, v48
	s_nop 2
	v_exp_f32_e32 v49, v49
	v_exp_f32_e32 v50, v50
	v_exp_f32_e32 v51, v51
	s_nop 2
	v_exp_f32_e32 v52, v52
	v_exp_f32_e32 v53, v53
	v_exp_f32_e32 v54, v54
	s_nop 2
	v_exp_f32_e32 v55, v55
	v_cvt_pk_bf16_f32 v242, v48, v49
	v_cvt_pk_bf16_f32 v243, v50, v51
	v_cvt_pk_bf16_f32 v244, v52, v53
	v_cvt_pk_bf16_f32 v245, v54, v55
	s_nop 2
	v_exp_f32_e32 v56, v56
	v_exp_f32_e32 v57, v57
	v_exp_f32_e32 v58, v58
	s_nop 2
	v_exp_f32_e32 v59, v59
	v_exp_f32_e32 v60, v60
	v_exp_f32_e32 v61, v61
	s_nop 2
	v_exp_f32_e32 v62, v62
	v_exp_f32_e32 v63, v63
	v_cvt_pk_bf16_f32 v246, v56, v57
	v_cvt_pk_bf16_f32 v247, v58, v59
	s_nop 2
	v_cvt_pk_bf16_f32 v248, v60, v61
	v_cvt_pk_bf16_f32 v249, v62, v63
	v_add_f32_e32 v172, v64, v65
	v_add_f32_e32 v173, v66, v67
	v_add_f32_e32 v177, v68, v69
	v_add_f32_e32 v64, v70, v71
	s_nop 2
	v_add_f32_e32 v172, v172, v72
	v_add_f32_e32 v173, v173, v73
	v_add_f32_e32 v177, v177, v74
	v_add_f32_e32 v64, v64, v75
	v_add_f32_e32 v172, v172, v76
	v_add_f32_e32 v173, v173, v77
	s_nop 2
	v_add_f32_e32 v177, v177, v78
	v_add_f32_e32 v64, v64, v79
	v_add_f32_e32 v172, v172, v48
	v_add_f32_e32 v173, v173, v49
	v_add_f32_e32 v177, v177, v50
	v_add_f32_e32 v64, v64, v51
	s_nop 2
	v_add_f32_e32 v172, v172, v52
	v_add_f32_e32 v173, v173, v53
	v_add_f32_e32 v177, v177, v54
	v_add_f32_e32 v64, v64, v55
	v_add_f32_e32 v172, v172, v56
	v_add_f32_e32 v173, v173, v57
	s_nop 2
	v_add_f32_e32 v177, v177, v58
	v_add_f32_e32 v64, v64, v59
	v_add_f32_e32 v172, v172, v60
	v_add_f32_e32 v173, v173, v61
	v_add_f32_e32 v177, v177, v62
	v_add_f32_e32 v64, v64, v63
	s_nop 2
	v_add_f32_e32 v172, v172, v173
	v_add_f32_e32 v177, v177, v64
	v_add_f32_e32 v172, v172, v177
	v_add_f32_e32 v157, v157, v172
	s_mov_b32 s14, 0x41000000
	s_mov_b32 s15, 0
	s_waitcnt lgkmcnt(0)
	s_barrier
	s_add_i32 s28, s28, 1
	s_cmp_lt_i32 s28, s22
	s_cbranch_scc1 .Lmla_A_loop
	v_mfma_f32_32x32x16_bf16 v[16:31], v[202:205], v[234:237], v[16:31]
	v_mfma_f32_32x32x16_bf16 v[0:15], v[218:221], v[234:237], v[0:15]
	v_mfma_f32_32x32x16_bf16 v[16:31], v[206:209], v[238:241], v[16:31]
	v_mfma_f32_32x32x16_bf16 v[0:15], v[222:225], v[238:241], v[0:15]
	v_mfma_f32_32x32x16_bf16 v[16:31], v[210:213], v[242:245], v[16:31]
	v_mfma_f32_32x32x16_bf16 v[0:15], v[226:229], v[242:245], v[0:15]
	v_mfma_f32_32x32x16_bf16 v[16:31], v[214:217], v[246:249], v[16:31]
	v_mfma_f32_32x32x16_bf16 v[0:15], v[230:233], v[246:249], v[0:15]
	s_branch .Lmla_exit
